# fused general sub-tile block without priority raise (the fused lean tile keeps its raise)
# baseline (speedup 1.0000x reference)
.Lfg0_k:
	v_add_u32_e32 v3, s76, v198
	ds_read_b128 v[4:7], v3
	v_add_u32_e32 v220, s76, v206
	ds_read_b128 v[8:11], v220
	v_add_u32_e32 v221, s76, v207
	ds_read_b128 v[12:15], v221
	v_add_u32_e32 v222, s76, v208
	ds_read_b128 v[214:217], v222
	s_and_b64 vcc, exec, s[80:81]
	s_cbranch_vccnz .Lfg0_tq
	s_waitcnt lgkmcnt(3)
	v_mfma_f32_32x32x16_bf16 v[118:133], v[4:7], v[134:137], v[86:101]
	s_waitcnt lgkmcnt(2)
	v_mfma_f32_32x32x16_bf16 v[118:133], v[8:11], v[138:141], v[118:133]
	s_waitcnt lgkmcnt(1)
	v_mfma_f32_32x32x16_bf16 v[118:133], v[12:15], v[142:145], v[118:133]
	s_waitcnt lgkmcnt(0)
	v_mfma_f32_32x32x16_bf16 v[118:133], v[214:217], v[150:153], v[118:133]
	v_mfma_f32_32x32x16_bf16 v[102:117], v[4:7], v[146:149], v[86:101]
	v_mfma_f32_32x32x16_bf16 v[102:117], v[8:11], v[154:157], v[102:117]
	v_mfma_f32_32x32x16_bf16 v[102:117], v[12:15], v[158:161], v[102:117]
	v_mfma_f32_32x32x16_bf16 v[102:117], v[214:217], v[162:165], v[102:117]
	s_branch .Lfg0_v

.Lfg0_tgo:
	s_waitcnt lgkmcnt(3)
	v_mfma_f32_32x32x16_bf16 v[118:133], v[4:7], v[134:137], v[118:133]
	s_waitcnt lgkmcnt(2)
	v_mfma_f32_32x32x16_bf16 v[118:133], v[8:11], v[138:141], v[118:133]
	s_waitcnt lgkmcnt(1)
	v_mfma_f32_32x32x16_bf16 v[118:133], v[12:15], v[142:145], v[118:133]
	s_waitcnt lgkmcnt(0)
	v_mfma_f32_32x32x16_bf16 v[118:133], v[214:217], v[150:153], v[118:133]
	v_mfma_f32_32x32x16_bf16 v[102:117], v[4:7], v[146:149], v[102:117]
	v_mfma_f32_32x32x16_bf16 v[102:117], v[8:11], v[154:157], v[102:117]
	v_mfma_f32_32x32x16_bf16 v[102:117], v[12:15], v[158:161], v[102:117]
	v_mfma_f32_32x32x16_bf16 v[102:117], v[214:217], v[162:165], v[102:117]

.Lfg0_nomask:
	s_nop 1
	v_exp_f32_e32 v118, v118
	v_exp_f32_e32 v119, v119
	v_exp_f32_e32 v120, v120
	v_exp_f32_e32 v121, v121
	v_exp_f32_e32 v122, v122
	v_exp_f32_e32 v123, v123
	v_exp_f32_e32 v124, v124
	v_exp_f32_e32 v125, v125
	v_exp_f32_e32 v126, v126
	v_exp_f32_e32 v127, v127
	v_exp_f32_e32 v128, v128
	v_exp_f32_e32 v129, v129
	v_exp_f32_e32 v130, v130
	v_exp_f32_e32 v131, v131
	v_exp_f32_e32 v132, v132
	v_exp_f32_e32 v133, v133
	v_pk_add_f32 v[16:17], v[118:119], v[120:121]
	v_pk_add_f32 v[16:17], v[16:17], v[122:123]
	v_pk_add_f32 v[16:17], v[16:17], v[124:125]
	v_cvt_pk_bf16_f32 v118, v118, v119
	v_cvt_pk_bf16_f32 v119, v120, v121
	v_cvt_pk_bf16_f32 v120, v122, v123
	v_cvt_pk_bf16_f32 v121, v124, v125
	v_cvt_pk_bf16_f32 v122, v126, v127
	v_cvt_pk_bf16_f32 v123, v128, v129
	v_cvt_pk_bf16_f32 v124, v130, v131
	v_cvt_pk_bf16_f32 v125, v132, v133
	v_pk_add_f32 v[16:17], v[16:17], v[126:127]
	v_pk_add_f32 v[16:17], v[16:17], v[128:129]
	v_pk_add_f32 v[16:17], v[16:17], v[130:131]
	v_pk_add_f32 v[16:17], v[16:17], v[132:133]
	s_waitcnt lgkmcnt(0)
	v_mfma_f32_32x32x16_bf16 v[20:35], v[234:237], v[118:121], v[20:35]
	v_exp_f32_e32 v102, v102
	v_exp_f32_e32 v103, v103
	v_exp_f32_e32 v104, v104
	v_mfma_f32_32x32x16_bf16 v[36:51], v[248:251], v[118:121], v[36:51]
	v_exp_f32_e32 v105, v105
	v_exp_f32_e32 v106, v106
	v_exp_f32_e32 v107, v107
	v_mfma_f32_32x32x16_bf16 v[20:35], v[244:247], v[122:125], v[20:35]
	v_exp_f32_e32 v108, v108
	v_exp_f32_e32 v109, v109
	v_exp_f32_e32 v110, v110
	v_mfma_f32_32x32x16_bf16 v[36:51], v[252:255], v[122:125], v[36:51]
	v_exp_f32_e32 v111, v111
	v_exp_f32_e32 v112, v112
	v_exp_f32_e32 v113, v113
	v_exp_f32_e32 v114, v114
	v_exp_f32_e32 v115, v115
	v_exp_f32_e32 v116, v116
	v_exp_f32_e32 v117, v117
	v_pk_add_f32 v[238:239], v[102:103], v[104:105]
	v_pk_add_f32 v[238:239], v[238:239], v[106:107]
	v_pk_add_f32 v[238:239], v[238:239], v[108:109]
	v_cvt_pk_bf16_f32 v102, v102, v103
	v_cvt_pk_bf16_f32 v103, v104, v105
	v_cvt_pk_bf16_f32 v104, v106, v107
	v_cvt_pk_bf16_f32 v105, v108, v109
	v_cvt_pk_bf16_f32 v106, v110, v111
	v_cvt_pk_bf16_f32 v107, v112, v113
	v_cvt_pk_bf16_f32 v108, v114, v115
	v_cvt_pk_bf16_f32 v109, v116, v117
	v_mfma_f32_32x32x16_bf16 v[68:83], v[234:237], v[102:105], v[68:83]
	v_pk_add_f32 v[238:239], v[238:239], v[110:111]
	v_pk_add_f32 v[238:239], v[238:239], v[112:113]
	v_mfma_f32_32x32x16_bf16 v[52:67], v[248:251], v[102:105], v[52:67]
	v_pk_add_f32 v[238:239], v[238:239], v[114:115]
	v_pk_add_f32 v[238:239], v[238:239], v[116:117]
	v_mfma_f32_32x32x16_bf16 v[68:83], v[244:247], v[106:109], v[68:83]
	v_add_f32_e32 v16, v16, v17
	v_mfma_f32_32x32x16_bf16 v[52:67], v[252:255], v[106:109], v[52:67]
	v_add_f32_e32 v180, v180, v16
	v_add_f32_e32 v238, v238, v239
	v_add_f32_e32 v181, v181, v238

.Lfg1_k:
	v_add_u32_e32 v3, s76, v198
	ds_read_b128 v[4:7], v3 offset:4096
	v_add_u32_e32 v220, s76, v206
	ds_read_b128 v[8:11], v220 offset:4096
	v_add_u32_e32 v221, s76, v207
	ds_read_b128 v[12:15], v221 offset:4096
	v_add_u32_e32 v222, s76, v208
	ds_read_b128 v[214:217], v222 offset:4096
	s_and_b64 vcc, exec, s[80:81]
	s_cbranch_vccnz .Lfg1_tq
	s_waitcnt lgkmcnt(3)
	v_mfma_f32_32x32x16_bf16 v[118:133], v[4:7], v[134:137], v[86:101]
	s_waitcnt lgkmcnt(2)
	v_mfma_f32_32x32x16_bf16 v[118:133], v[8:11], v[138:141], v[118:133]
	s_waitcnt lgkmcnt(1)
	v_mfma_f32_32x32x16_bf16 v[118:133], v[12:15], v[142:145], v[118:133]
	s_waitcnt lgkmcnt(0)
	v_mfma_f32_32x32x16_bf16 v[118:133], v[214:217], v[150:153], v[118:133]
	v_mfma_f32_32x32x16_bf16 v[102:117], v[4:7], v[146:149], v[86:101]
	v_mfma_f32_32x32x16_bf16 v[102:117], v[8:11], v[154:157], v[102:117]
	v_mfma_f32_32x32x16_bf16 v[102:117], v[12:15], v[158:161], v[102:117]
	v_mfma_f32_32x32x16_bf16 v[102:117], v[214:217], v[162:165], v[102:117]
	s_branch .Lfg1_v

.Lfg1_nomask:
	s_nop 1
	v_exp_f32_e32 v118, v118
	v_exp_f32_e32 v119, v119
	v_exp_f32_e32 v120, v120
	v_exp_f32_e32 v121, v121
	v_exp_f32_e32 v122, v122
	v_exp_f32_e32 v123, v123
	v_exp_f32_e32 v124, v124
	v_exp_f32_e32 v125, v125
	v_exp_f32_e32 v126, v126
	v_exp_f32_e32 v127, v127
	v_exp_f32_e32 v128, v128
	v_exp_f32_e32 v129, v129
	v_exp_f32_e32 v130, v130
	v_exp_f32_e32 v131, v131
	v_exp_f32_e32 v132, v132
	v_exp_f32_e32 v133, v133
	v_pk_add_f32 v[16:17], v[118:119], v[120:121]
	v_pk_add_f32 v[16:17], v[16:17], v[122:123]
	v_pk_add_f32 v[16:17], v[16:17], v[124:125]
	v_cvt_pk_bf16_f32 v118, v118, v119
	v_cvt_pk_bf16_f32 v119, v120, v121
	v_cvt_pk_bf16_f32 v120, v122, v123
	v_cvt_pk_bf16_f32 v121, v124, v125
	v_cvt_pk_bf16_f32 v122, v126, v127
	v_cvt_pk_bf16_f32 v123, v128, v129
	v_cvt_pk_bf16_f32 v124, v130, v131
	v_cvt_pk_bf16_f32 v125, v132, v133
	v_pk_add_f32 v[16:17], v[16:17], v[126:127]
	v_pk_add_f32 v[16:17], v[16:17], v[128:129]
	v_pk_add_f32 v[16:17], v[16:17], v[130:131]
	v_pk_add_f32 v[16:17], v[16:17], v[132:133]
	s_waitcnt lgkmcnt(0)
	v_mfma_f32_32x32x16_bf16 v[20:35], v[234:237], v[118:121], v[20:35]
	v_exp_f32_e32 v102, v102
	v_exp_f32_e32 v103, v103
	v_exp_f32_e32 v104, v104
	v_mfma_f32_32x32x16_bf16 v[36:51], v[248:251], v[118:121], v[36:51]
	v_exp_f32_e32 v105, v105
	v_exp_f32_e32 v106, v106
	v_exp_f32_e32 v107, v107
	v_mfma_f32_32x32x16_bf16 v[20:35], v[244:247], v[122:125], v[20:35]
	v_exp_f32_e32 v108, v108
	v_exp_f32_e32 v109, v109
	v_exp_f32_e32 v110, v110
	v_mfma_f32_32x32x16_bf16 v[36:51], v[252:255], v[122:125], v[36:51]
	v_exp_f32_e32 v111, v111
	v_exp_f32_e32 v112, v112
	v_exp_f32_e32 v113, v113
	v_exp_f32_e32 v114, v114
	v_exp_f32_e32 v115, v115
	v_exp_f32_e32 v116, v116
	v_exp_f32_e32 v117, v117
	v_pk_add_f32 v[238:239], v[102:103], v[104:105]
	v_pk_add_f32 v[238:239], v[238:239], v[106:107]
	v_pk_add_f32 v[238:239], v[238:239], v[108:109]
	v_cvt_pk_bf16_f32 v102, v102, v103
	v_cvt_pk_bf16_f32 v103, v104, v105
	v_cvt_pk_bf16_f32 v104, v106, v107
	v_cvt_pk_bf16_f32 v105, v108, v109
	v_cvt_pk_bf16_f32 v106, v110, v111
	v_cvt_pk_bf16_f32 v107, v112, v113
	v_cvt_pk_bf16_f32 v108, v114, v115
	v_cvt_pk_bf16_f32 v109, v116, v117
	v_mfma_f32_32x32x16_bf16 v[68:83], v[234:237], v[102:105], v[68:83]
	v_pk_add_f32 v[238:239], v[238:239], v[110:111]
	v_pk_add_f32 v[238:239], v[238:239], v[112:113]
	v_mfma_f32_32x32x16_bf16 v[52:67], v[248:251], v[102:105], v[52:67]
	v_pk_add_f32 v[238:239], v[238:239], v[114:115]
	v_pk_add_f32 v[238:239], v[238:239], v[116:117]
	v_mfma_f32_32x32x16_bf16 v[68:83], v[244:247], v[106:109], v[68:83]
	v_add_f32_e32 v16, v16, v17
	v_mfma_f32_32x32x16_bf16 v[52:67], v[252:255], v[106:109], v[52:67]
	v_add_f32_e32 v180, v180, v16
	v_add_f32_e32 v238, v238, v239
	v_add_f32_e32 v181, v181, v238
	s_branch .LBB0_653
